# setup phase: silu(cond) staging loop de-serialised (36 loads in flight, then 36 silu/LDS stores with counted waits)
# baseline (speedup 1.0000x reference)
.LBB0_20:
	s_barrier
	s_and_saveexec_b64 s[8:9], s[6:7]
	s_load_dwordx16 s[56:71], s[0:1], 0x0
	s_cbranch_execz .LBB0_23
	s_mov_b64 s[12:13], 0
	v_mov_b64_e32 v[0:1], v[150:151]
	v_mov_b32_e32 v2, v191
	v_mov_b32_e32 v3, v144
	s_waitcnt lgkmcnt(0)
	v_and_b32_e32 v4, 0x3ff, v3
	v_lshlrev_b32_e32 v146, 2, v4
	v_lshl_add_u64 v[4:5], s[62:63], 0, v[146:147]
	v_cmp_gt_i32_e32 vcc, s17, v3
	s_nop 1
	v_cndmask_b32_e32 v5, v5, v1, vcc
	v_cndmask_b32_e32 v4, v4, v0, vcc
	global_load_dword v214, v[4:5], off
	v_add_u32_e32 v3, 0x100, v3
	v_lshl_add_u64 v[0:1], v[0:1], 0, s[2:3]
	v_and_b32_e32 v4, 0x3ff, v3
	v_lshlrev_b32_e32 v146, 2, v4
	v_lshl_add_u64 v[4:5], s[62:63], 0, v[146:147]
	v_cmp_gt_i32_e32 vcc, s17, v3
	s_nop 1
	v_cndmask_b32_e32 v5, v5, v1, vcc
	v_cndmask_b32_e32 v4, v4, v0, vcc
	global_load_dword v215, v[4:5], off
	v_add_u32_e32 v3, 0x100, v3
	v_lshl_add_u64 v[0:1], v[0:1], 0, s[2:3]
	v_and_b32_e32 v4, 0x3ff, v3
	v_lshlrev_b32_e32 v146, 2, v4
	v_lshl_add_u64 v[4:5], s[62:63], 0, v[146:147]
	v_cmp_gt_i32_e32 vcc, s17, v3
	s_nop 1
	v_cndmask_b32_e32 v5, v5, v1, vcc
	v_cndmask_b32_e32 v4, v4, v0, vcc
	global_load_dword v216, v[4:5], off
	v_add_u32_e32 v3, 0x100, v3
	v_lshl_add_u64 v[0:1], v[0:1], 0, s[2:3]
	v_and_b32_e32 v4, 0x3ff, v3
	v_lshlrev_b32_e32 v146, 2, v4
	v_lshl_add_u64 v[4:5], s[62:63], 0, v[146:147]
	v_cmp_gt_i32_e32 vcc, s17, v3
	s_nop 1
	v_cndmask_b32_e32 v5, v5, v1, vcc
	v_cndmask_b32_e32 v4, v4, v0, vcc
	global_load_dword v217, v[4:5], off
	v_add_u32_e32 v3, 0x100, v3
	v_lshl_add_u64 v[0:1], v[0:1], 0, s[2:3]
	v_and_b32_e32 v4, 0x3ff, v3
	v_lshlrev_b32_e32 v146, 2, v4
	v_lshl_add_u64 v[4:5], s[62:63], 0, v[146:147]
	v_cmp_gt_i32_e32 vcc, s17, v3
	s_nop 1
	v_cndmask_b32_e32 v5, v5, v1, vcc
	v_cndmask_b32_e32 v4, v4, v0, vcc
	global_load_dword v218, v[4:5], off
	v_add_u32_e32 v3, 0x100, v3
	v_lshl_add_u64 v[0:1], v[0:1], 0, s[2:3]
	v_and_b32_e32 v4, 0x3ff, v3
	v_lshlrev_b32_e32 v146, 2, v4
	v_lshl_add_u64 v[4:5], s[62:63], 0, v[146:147]
	v_cmp_gt_i32_e32 vcc, s17, v3
	s_nop 1
	v_cndmask_b32_e32 v5, v5, v1, vcc
	v_cndmask_b32_e32 v4, v4, v0, vcc
	global_load_dword v219, v[4:5], off
	v_add_u32_e32 v3, 0x100, v3
	v_lshl_add_u64 v[0:1], v[0:1], 0, s[2:3]
	v_and_b32_e32 v4, 0x3ff, v3
	v_lshlrev_b32_e32 v146, 2, v4
	v_lshl_add_u64 v[4:5], s[62:63], 0, v[146:147]
	v_cmp_gt_i32_e32 vcc, s17, v3
	s_nop 1
	v_cndmask_b32_e32 v5, v5, v1, vcc
	v_cndmask_b32_e32 v4, v4, v0, vcc
	global_load_dword v220, v[4:5], off
	v_add_u32_e32 v3, 0x100, v3
	v_lshl_add_u64 v[0:1], v[0:1], 0, s[2:3]
	v_and_b32_e32 v4, 0x3ff, v3
	v_lshlrev_b32_e32 v146, 2, v4
	v_lshl_add_u64 v[4:5], s[62:63], 0, v[146:147]
	v_cmp_gt_i32_e32 vcc, s17, v3
	s_nop 1
	v_cndmask_b32_e32 v5, v5, v1, vcc
	v_cndmask_b32_e32 v4, v4, v0, vcc
	global_load_dword v221, v[4:5], off
	v_add_u32_e32 v3, 0x100, v3
	v_lshl_add_u64 v[0:1], v[0:1], 0, s[2:3]
	v_and_b32_e32 v4, 0x3ff, v3
	v_lshlrev_b32_e32 v146, 2, v4
	v_lshl_add_u64 v[4:5], s[62:63], 0, v[146:147]
	v_cmp_gt_i32_e32 vcc, s17, v3
	s_nop 1
	v_cndmask_b32_e32 v5, v5, v1, vcc
	v_cndmask_b32_e32 v4, v4, v0, vcc
	global_load_dword v222, v[4:5], off
	v_add_u32_e32 v3, 0x100, v3
	v_lshl_add_u64 v[0:1], v[0:1], 0, s[2:3]
	v_and_b32_e32 v4, 0x3ff, v3
	v_lshlrev_b32_e32 v146, 2, v4
	v_lshl_add_u64 v[4:5], s[62:63], 0, v[146:147]
	v_cmp_gt_i32_e32 vcc, s17, v3
	s_nop 1
	v_cndmask_b32_e32 v5, v5, v1, vcc
	v_cndmask_b32_e32 v4, v4, v0, vcc
	global_load_dword v223, v[4:5], off
	v_add_u32_e32 v3, 0x100, v3
	v_lshl_add_u64 v[0:1], v[0:1], 0, s[2:3]
	v_and_b32_e32 v4, 0x3ff, v3
	v_lshlrev_b32_e32 v146, 2, v4
	v_lshl_add_u64 v[4:5], s[62:63], 0, v[146:147]
	v_cmp_gt_i32_e32 vcc, s17, v3
	s_nop 1
	v_cndmask_b32_e32 v5, v5, v1, vcc
	v_cndmask_b32_e32 v4, v4, v0, vcc
	global_load_dword v224, v[4:5], off
	v_add_u32_e32 v3, 0x100, v3
	v_lshl_add_u64 v[0:1], v[0:1], 0, s[2:3]
	v_and_b32_e32 v4, 0x3ff, v3
	v_lshlrev_b32_e32 v146, 2, v4
	v_lshl_add_u64 v[4:5], s[62:63], 0, v[146:147]
	v_cmp_gt_i32_e32 vcc, s17, v3
	s_nop 1
	v_cndmask_b32_e32 v5, v5, v1, vcc
	v_cndmask_b32_e32 v4, v4, v0, vcc
	global_load_dword v225, v[4:5], off
	v_add_u32_e32 v3, 0x100, v3
	v_lshl_add_u64 v[0:1], v[0:1], 0, s[2:3]
	v_and_b32_e32 v4, 0x3ff, v3
	v_lshlrev_b32_e32 v146, 2, v4
	v_lshl_add_u64 v[4:5], s[62:63], 0, v[146:147]
	v_cmp_gt_i32_e32 vcc, s17, v3
	s_nop 1
	v_cndmask_b32_e32 v5, v5, v1, vcc
	v_cndmask_b32_e32 v4, v4, v0, vcc
	global_load_dword v226, v[4:5], off
	v_add_u32_e32 v3, 0x100, v3
	v_lshl_add_u64 v[0:1], v[0:1], 0, s[2:3]
	v_and_b32_e32 v4, 0x3ff, v3
	v_lshlrev_b32_e32 v146, 2, v4
	v_lshl_add_u64 v[4:5], s[62:63], 0, v[146:147]
	v_cmp_gt_i32_e32 vcc, s17, v3
	s_nop 1
	v_cndmask_b32_e32 v5, v5, v1, vcc
	v_cndmask_b32_e32 v4, v4, v0, vcc
	global_load_dword v227, v[4:5], off
	v_add_u32_e32 v3, 0x100, v3
	v_lshl_add_u64 v[0:1], v[0:1], 0, s[2:3]
	v_and_b32_e32 v4, 0x3ff, v3
	v_lshlrev_b32_e32 v146, 2, v4
	v_lshl_add_u64 v[4:5], s[62:63], 0, v[146:147]
	v_cmp_gt_i32_e32 vcc, s17, v3
	s_nop 1
	v_cndmask_b32_e32 v5, v5, v1, vcc
	v_cndmask_b32_e32 v4, v4, v0, vcc
	global_load_dword v228, v[4:5], off
	v_add_u32_e32 v3, 0x100, v3
	v_lshl_add_u64 v[0:1], v[0:1], 0, s[2:3]
	v_and_b32_e32 v4, 0x3ff, v3
	v_lshlrev_b32_e32 v146, 2, v4
	v_lshl_add_u64 v[4:5], s[62:63], 0, v[146:147]
	v_cmp_gt_i32_e32 vcc, s17, v3
	s_nop 1
	v_cndmask_b32_e32 v5, v5, v1, vcc
	v_cndmask_b32_e32 v4, v4, v0, vcc
	global_load_dword v229, v[4:5], off
	v_add_u32_e32 v3, 0x100, v3
	v_lshl_add_u64 v[0:1], v[0:1], 0, s[2:3]
	v_and_b32_e32 v4, 0x3ff, v3
	v_lshlrev_b32_e32 v146, 2, v4
	v_lshl_add_u64 v[4:5], s[62:63], 0, v[146:147]
	v_cmp_gt_i32_e32 vcc, s17, v3
	s_nop 1
	v_cndmask_b32_e32 v5, v5, v1, vcc
	v_cndmask_b32_e32 v4, v4, v0, vcc
	global_load_dword v230, v[4:5], off
	v_add_u32_e32 v3, 0x100, v3
	v_lshl_add_u64 v[0:1], v[0:1], 0, s[2:3]
	v_and_b32_e32 v4, 0x3ff, v3
	v_lshlrev_b32_e32 v146, 2, v4
	v_lshl_add_u64 v[4:5], s[62:63], 0, v[146:147]
	v_cmp_gt_i32_e32 vcc, s17, v3
	s_nop 1
	v_cndmask_b32_e32 v5, v5, v1, vcc
	v_cndmask_b32_e32 v4, v4, v0, vcc
	global_load_dword v231, v[4:5], off
	v_add_u32_e32 v3, 0x100, v3
	v_lshl_add_u64 v[0:1], v[0:1], 0, s[2:3]
	v_and_b32_e32 v4, 0x3ff, v3
	v_lshlrev_b32_e32 v146, 2, v4
	v_lshl_add_u64 v[4:5], s[62:63], 0, v[146:147]
	v_cmp_gt_i32_e32 vcc, s17, v3
	s_nop 1
	v_cndmask_b32_e32 v5, v5, v1, vcc
	v_cndmask_b32_e32 v4, v4, v0, vcc
	global_load_dword v232, v[4:5], off
	v_add_u32_e32 v3, 0x100, v3
	v_lshl_add_u64 v[0:1], v[0:1], 0, s[2:3]
	v_and_b32_e32 v4, 0x3ff, v3
	v_lshlrev_b32_e32 v146, 2, v4
	v_lshl_add_u64 v[4:5], s[62:63], 0, v[146:147]
	v_cmp_gt_i32_e32 vcc, s17, v3
	s_nop 1
	v_cndmask_b32_e32 v5, v5, v1, vcc
	v_cndmask_b32_e32 v4, v4, v0, vcc
	global_load_dword v233, v[4:5], off
	v_add_u32_e32 v3, 0x100, v3
	v_lshl_add_u64 v[0:1], v[0:1], 0, s[2:3]
	v_and_b32_e32 v4, 0x3ff, v3
	v_lshlrev_b32_e32 v146, 2, v4
	v_lshl_add_u64 v[4:5], s[62:63], 0, v[146:147]
	v_cmp_gt_i32_e32 vcc, s17, v3
	s_nop 1
	v_cndmask_b32_e32 v5, v5, v1, vcc
	v_cndmask_b32_e32 v4, v4, v0, vcc
	global_load_dword v234, v[4:5], off
	v_add_u32_e32 v3, 0x100, v3
	v_lshl_add_u64 v[0:1], v[0:1], 0, s[2:3]
	v_and_b32_e32 v4, 0x3ff, v3
	v_lshlrev_b32_e32 v146, 2, v4
	v_lshl_add_u64 v[4:5], s[62:63], 0, v[146:147]
	v_cmp_gt_i32_e32 vcc, s17, v3
	s_nop 1
	v_cndmask_b32_e32 v5, v5, v1, vcc
	v_cndmask_b32_e32 v4, v4, v0, vcc
	global_load_dword v235, v[4:5], off
	v_add_u32_e32 v3, 0x100, v3
	v_lshl_add_u64 v[0:1], v[0:1], 0, s[2:3]
	v_and_b32_e32 v4, 0x3ff, v3
	v_lshlrev_b32_e32 v146, 2, v4
	v_lshl_add_u64 v[4:5], s[62:63], 0, v[146:147]
	v_cmp_gt_i32_e32 vcc, s17, v3
	s_nop 1
	v_cndmask_b32_e32 v5, v5, v1, vcc
	v_cndmask_b32_e32 v4, v4, v0, vcc
	global_load_dword v236, v[4:5], off
	v_add_u32_e32 v3, 0x100, v3
	v_lshl_add_u64 v[0:1], v[0:1], 0, s[2:3]
	v_and_b32_e32 v4, 0x3ff, v3
	v_lshlrev_b32_e32 v146, 2, v4
	v_lshl_add_u64 v[4:5], s[62:63], 0, v[146:147]
	v_cmp_gt_i32_e32 vcc, s17, v3
	s_nop 1
	v_cndmask_b32_e32 v5, v5, v1, vcc
	v_cndmask_b32_e32 v4, v4, v0, vcc
	global_load_dword v237, v[4:5], off
	v_add_u32_e32 v3, 0x100, v3
	v_lshl_add_u64 v[0:1], v[0:1], 0, s[2:3]
	v_and_b32_e32 v4, 0x3ff, v3
	v_lshlrev_b32_e32 v146, 2, v4
	v_lshl_add_u64 v[4:5], s[62:63], 0, v[146:147]
	v_cmp_gt_i32_e32 vcc, s17, v3
	s_nop 1
	v_cndmask_b32_e32 v5, v5, v1, vcc
	v_cndmask_b32_e32 v4, v4, v0, vcc
	global_load_dword v238, v[4:5], off
	v_add_u32_e32 v3, 0x100, v3
	v_lshl_add_u64 v[0:1], v[0:1], 0, s[2:3]
	v_and_b32_e32 v4, 0x3ff, v3
	v_lshlrev_b32_e32 v146, 2, v4
	v_lshl_add_u64 v[4:5], s[62:63], 0, v[146:147]
	v_cmp_gt_i32_e32 vcc, s17, v3
	s_nop 1
	v_cndmask_b32_e32 v5, v5, v1, vcc
	v_cndmask_b32_e32 v4, v4, v0, vcc
	global_load_dword v239, v[4:5], off
	v_add_u32_e32 v3, 0x100, v3
	v_lshl_add_u64 v[0:1], v[0:1], 0, s[2:3]
	v_and_b32_e32 v4, 0x3ff, v3
	v_lshlrev_b32_e32 v146, 2, v4
	v_lshl_add_u64 v[4:5], s[62:63], 0, v[146:147]
	v_cmp_gt_i32_e32 vcc, s17, v3
	s_nop 1
	v_cndmask_b32_e32 v5, v5, v1, vcc
	v_cndmask_b32_e32 v4, v4, v0, vcc
	global_load_dword v240, v[4:5], off
	v_add_u32_e32 v3, 0x100, v3
	v_lshl_add_u64 v[0:1], v[0:1], 0, s[2:3]
	v_and_b32_e32 v4, 0x3ff, v3
	v_lshlrev_b32_e32 v146, 2, v4
	v_lshl_add_u64 v[4:5], s[62:63], 0, v[146:147]
	v_cmp_gt_i32_e32 vcc, s17, v3
	s_nop 1
	v_cndmask_b32_e32 v5, v5, v1, vcc
	v_cndmask_b32_e32 v4, v4, v0, vcc
	global_load_dword v241, v[4:5], off
	v_add_u32_e32 v3, 0x100, v3
	v_lshl_add_u64 v[0:1], v[0:1], 0, s[2:3]
	v_and_b32_e32 v4, 0x3ff, v3
	v_lshlrev_b32_e32 v146, 2, v4
	v_lshl_add_u64 v[4:5], s[62:63], 0, v[146:147]
	v_cmp_gt_i32_e32 vcc, s17, v3
	s_nop 1
	v_cndmask_b32_e32 v5, v5, v1, vcc
	v_cndmask_b32_e32 v4, v4, v0, vcc
	global_load_dword v242, v[4:5], off
	v_add_u32_e32 v3, 0x100, v3
	v_lshl_add_u64 v[0:1], v[0:1], 0, s[2:3]
	v_and_b32_e32 v4, 0x3ff, v3
	v_lshlrev_b32_e32 v146, 2, v4
	v_lshl_add_u64 v[4:5], s[62:63], 0, v[146:147]
	v_cmp_gt_i32_e32 vcc, s17, v3
	s_nop 1
	v_cndmask_b32_e32 v5, v5, v1, vcc
	v_cndmask_b32_e32 v4, v4, v0, vcc
	global_load_dword v243, v[4:5], off
	v_add_u32_e32 v3, 0x100, v3
	v_lshl_add_u64 v[0:1], v[0:1], 0, s[2:3]
	v_and_b32_e32 v4, 0x3ff, v3
	v_lshlrev_b32_e32 v146, 2, v4
	v_lshl_add_u64 v[4:5], s[62:63], 0, v[146:147]
	v_cmp_gt_i32_e32 vcc, s17, v3
	s_nop 1
	v_cndmask_b32_e32 v5, v5, v1, vcc
	v_cndmask_b32_e32 v4, v4, v0, vcc
	global_load_dword v244, v[4:5], off
	v_add_u32_e32 v3, 0x100, v3
	v_lshl_add_u64 v[0:1], v[0:1], 0, s[2:3]
	v_and_b32_e32 v4, 0x3ff, v3
	v_lshlrev_b32_e32 v146, 2, v4
	v_lshl_add_u64 v[4:5], s[62:63], 0, v[146:147]
	v_cmp_gt_i32_e32 vcc, s17, v3
	s_nop 1
	v_cndmask_b32_e32 v5, v5, v1, vcc
	v_cndmask_b32_e32 v4, v4, v0, vcc
	global_load_dword v245, v[4:5], off
	v_add_u32_e32 v3, 0x100, v3
	v_lshl_add_u64 v[0:1], v[0:1], 0, s[2:3]
	v_and_b32_e32 v4, 0x3ff, v3
	v_lshlrev_b32_e32 v146, 2, v4
	v_lshl_add_u64 v[4:5], s[62:63], 0, v[146:147]
	v_cmp_gt_i32_e32 vcc, s17, v3
	s_nop 1
	v_cndmask_b32_e32 v5, v5, v1, vcc
	v_cndmask_b32_e32 v4, v4, v0, vcc
	global_load_dword v246, v[4:5], off
	v_add_u32_e32 v3, 0x100, v3
	v_lshl_add_u64 v[0:1], v[0:1], 0, s[2:3]
	v_and_b32_e32 v4, 0x3ff, v3
	v_lshlrev_b32_e32 v146, 2, v4
	v_lshl_add_u64 v[4:5], s[62:63], 0, v[146:147]
	v_cmp_gt_i32_e32 vcc, s17, v3
	s_nop 1
	v_cndmask_b32_e32 v5, v5, v1, vcc
	v_cndmask_b32_e32 v4, v4, v0, vcc
	global_load_dword v247, v[4:5], off
	v_add_u32_e32 v3, 0x100, v3
	v_lshl_add_u64 v[0:1], v[0:1], 0, s[2:3]
	v_and_b32_e32 v4, 0x3ff, v3
	v_lshlrev_b32_e32 v146, 2, v4
	v_lshl_add_u64 v[4:5], s[62:63], 0, v[146:147]
	v_cmp_gt_i32_e32 vcc, s17, v3
	s_nop 1
	v_cndmask_b32_e32 v5, v5, v1, vcc
	v_cndmask_b32_e32 v4, v4, v0, vcc
	global_load_dword v248, v[4:5], off
	v_add_u32_e32 v3, 0x100, v3
	v_lshl_add_u64 v[0:1], v[0:1], 0, s[2:3]
	v_and_b32_e32 v4, 0x3ff, v3
	v_lshlrev_b32_e32 v146, 2, v4
	v_lshl_add_u64 v[4:5], s[62:63], 0, v[146:147]
	v_cmp_gt_i32_e32 vcc, s17, v3
	s_nop 1
	v_cndmask_b32_e32 v5, v5, v1, vcc
	v_cndmask_b32_e32 v4, v4, v0, vcc
	global_load_dword v249, v[4:5], off
	v_add_u32_e32 v3, 0x100, v3
	v_lshl_add_u64 v[0:1], v[0:1], 0, s[2:3]
	s_waitcnt vmcnt(35)
	v_mov_b32_e32 v4, v214
	v_mul_f32_e32 v5, 0xbfb8aa3b, v4
	v_exp_f32_e32 v5, v5
	s_nop 0
	v_add_f32_e32 v5, 1.0, v5
	v_div_scale_f32 v6, s[14:15], v5, v5, v4
	v_rcp_f32_e32 v7, v6
	v_div_scale_f32 v8, vcc, v4, v5, v4
	v_fma_f32 v9, -v6, v7, 1.0
	v_fmac_f32_e32 v7, v9, v7
	v_mul_f32_e32 v9, v8, v7
	v_fma_f32 v10, -v6, v9, v8
	v_fmac_f32_e32 v9, v10, v7
	v_fma_f32 v6, -v6, v9, v8
	v_div_fmas_f32 v6, v6, v7, v9
	v_div_fixup_f32 v4, v6, v5, v4
	ds_write_b32 v2, v4
	v_add_u32_e32 v2, 0x400, v2
	s_waitcnt vmcnt(34)
	v_mov_b32_e32 v4, v215
	v_mul_f32_e32 v5, 0xbfb8aa3b, v4
	v_exp_f32_e32 v5, v5
	s_nop 0
	v_add_f32_e32 v5, 1.0, v5
	v_div_scale_f32 v6, s[14:15], v5, v5, v4
	v_rcp_f32_e32 v7, v6
	v_div_scale_f32 v8, vcc, v4, v5, v4
	v_fma_f32 v9, -v6, v7, 1.0
	v_fmac_f32_e32 v7, v9, v7
	v_mul_f32_e32 v9, v8, v7
	v_fma_f32 v10, -v6, v9, v8
	v_fmac_f32_e32 v9, v10, v7
	v_fma_f32 v6, -v6, v9, v8
	v_div_fmas_f32 v6, v6, v7, v9
	v_div_fixup_f32 v4, v6, v5, v4
	ds_write_b32 v2, v4
	v_add_u32_e32 v2, 0x400, v2
	s_waitcnt vmcnt(33)
	v_mov_b32_e32 v4, v216
	v_mul_f32_e32 v5, 0xbfb8aa3b, v4
	v_exp_f32_e32 v5, v5
	s_nop 0
	v_add_f32_e32 v5, 1.0, v5
	v_div_scale_f32 v6, s[14:15], v5, v5, v4
	v_rcp_f32_e32 v7, v6
	v_div_scale_f32 v8, vcc, v4, v5, v4
	v_fma_f32 v9, -v6, v7, 1.0
	v_fmac_f32_e32 v7, v9, v7
	v_mul_f32_e32 v9, v8, v7
	v_fma_f32 v10, -v6, v9, v8
	v_fmac_f32_e32 v9, v10, v7
	v_fma_f32 v6, -v6, v9, v8
	v_div_fmas_f32 v6, v6, v7, v9
	v_div_fixup_f32 v4, v6, v5, v4
	ds_write_b32 v2, v4
	v_add_u32_e32 v2, 0x400, v2
	s_waitcnt vmcnt(32)
	v_mov_b32_e32 v4, v217
	v_mul_f32_e32 v5, 0xbfb8aa3b, v4
	v_exp_f32_e32 v5, v5
	s_nop 0
	v_add_f32_e32 v5, 1.0, v5
	v_div_scale_f32 v6, s[14:15], v5, v5, v4
	v_rcp_f32_e32 v7, v6
	v_div_scale_f32 v8, vcc, v4, v5, v4
	v_fma_f32 v9, -v6, v7, 1.0
	v_fmac_f32_e32 v7, v9, v7
	v_mul_f32_e32 v9, v8, v7
	v_fma_f32 v10, -v6, v9, v8
	v_fmac_f32_e32 v9, v10, v7
	v_fma_f32 v6, -v6, v9, v8
	v_div_fmas_f32 v6, v6, v7, v9
	v_div_fixup_f32 v4, v6, v5, v4
	ds_write_b32 v2, v4
	v_add_u32_e32 v2, 0x400, v2
	s_waitcnt vmcnt(31)
	v_mov_b32_e32 v4, v218
	v_mul_f32_e32 v5, 0xbfb8aa3b, v4
	v_exp_f32_e32 v5, v5
	s_nop 0
	v_add_f32_e32 v5, 1.0, v5
	v_div_scale_f32 v6, s[14:15], v5, v5, v4
	v_rcp_f32_e32 v7, v6
	v_div_scale_f32 v8, vcc, v4, v5, v4
	v_fma_f32 v9, -v6, v7, 1.0
	v_fmac_f32_e32 v7, v9, v7
	v_mul_f32_e32 v9, v8, v7
	v_fma_f32 v10, -v6, v9, v8
	v_fmac_f32_e32 v9, v10, v7
	v_fma_f32 v6, -v6, v9, v8
	v_div_fmas_f32 v6, v6, v7, v9
	v_div_fixup_f32 v4, v6, v5, v4
	ds_write_b32 v2, v4
	v_add_u32_e32 v2, 0x400, v2
	s_waitcnt vmcnt(30)
	v_mov_b32_e32 v4, v219
	v_mul_f32_e32 v5, 0xbfb8aa3b, v4
	v_exp_f32_e32 v5, v5
	s_nop 0
	v_add_f32_e32 v5, 1.0, v5
	v_div_scale_f32 v6, s[14:15], v5, v5, v4
	v_rcp_f32_e32 v7, v6
	v_div_scale_f32 v8, vcc, v4, v5, v4
	v_fma_f32 v9, -v6, v7, 1.0
	v_fmac_f32_e32 v7, v9, v7
	v_mul_f32_e32 v9, v8, v7
	v_fma_f32 v10, -v6, v9, v8
	v_fmac_f32_e32 v9, v10, v7
	v_fma_f32 v6, -v6, v9, v8
	v_div_fmas_f32 v6, v6, v7, v9
	v_div_fixup_f32 v4, v6, v5, v4
	ds_write_b32 v2, v4
	v_add_u32_e32 v2, 0x400, v2
	s_waitcnt vmcnt(29)
	v_mov_b32_e32 v4, v220
	v_mul_f32_e32 v5, 0xbfb8aa3b, v4
	v_exp_f32_e32 v5, v5
	s_nop 0
	v_add_f32_e32 v5, 1.0, v5
	v_div_scale_f32 v6, s[14:15], v5, v5, v4
	v_rcp_f32_e32 v7, v6
	v_div_scale_f32 v8, vcc, v4, v5, v4
	v_fma_f32 v9, -v6, v7, 1.0
	v_fmac_f32_e32 v7, v9, v7
	v_mul_f32_e32 v9, v8, v7
	v_fma_f32 v10, -v6, v9, v8
	v_fmac_f32_e32 v9, v10, v7
	v_fma_f32 v6, -v6, v9, v8
	v_div_fmas_f32 v6, v6, v7, v9
	v_div_fixup_f32 v4, v6, v5, v4
	ds_write_b32 v2, v4
	v_add_u32_e32 v2, 0x400, v2
	s_waitcnt vmcnt(28)
	v_mov_b32_e32 v4, v221
	v_mul_f32_e32 v5, 0xbfb8aa3b, v4
	v_exp_f32_e32 v5, v5
	s_nop 0
	v_add_f32_e32 v5, 1.0, v5
	v_div_scale_f32 v6, s[14:15], v5, v5, v4
	v_rcp_f32_e32 v7, v6
	v_div_scale_f32 v8, vcc, v4, v5, v4
	v_fma_f32 v9, -v6, v7, 1.0
	v_fmac_f32_e32 v7, v9, v7
	v_mul_f32_e32 v9, v8, v7
	v_fma_f32 v10, -v6, v9, v8
	v_fmac_f32_e32 v9, v10, v7
	v_fma_f32 v6, -v6, v9, v8
	v_div_fmas_f32 v6, v6, v7, v9
	v_div_fixup_f32 v4, v6, v5, v4
	ds_write_b32 v2, v4
	v_add_u32_e32 v2, 0x400, v2
	s_waitcnt vmcnt(27)
	v_mov_b32_e32 v4, v222
	v_mul_f32_e32 v5, 0xbfb8aa3b, v4
	v_exp_f32_e32 v5, v5
	s_nop 0
	v_add_f32_e32 v5, 1.0, v5
	v_div_scale_f32 v6, s[14:15], v5, v5, v4
	v_rcp_f32_e32 v7, v6
	v_div_scale_f32 v8, vcc, v4, v5, v4
	v_fma_f32 v9, -v6, v7, 1.0
	v_fmac_f32_e32 v7, v9, v7
	v_mul_f32_e32 v9, v8, v7
	v_fma_f32 v10, -v6, v9, v8
	v_fmac_f32_e32 v9, v10, v7
	v_fma_f32 v6, -v6, v9, v8
	v_div_fmas_f32 v6, v6, v7, v9
	v_div_fixup_f32 v4, v6, v5, v4
	ds_write_b32 v2, v4
	v_add_u32_e32 v2, 0x400, v2
	s_waitcnt vmcnt(26)
	v_mov_b32_e32 v4, v223
	v_mul_f32_e32 v5, 0xbfb8aa3b, v4
	v_exp_f32_e32 v5, v5
	s_nop 0
	v_add_f32_e32 v5, 1.0, v5
	v_div_scale_f32 v6, s[14:15], v5, v5, v4
	v_rcp_f32_e32 v7, v6
	v_div_scale_f32 v8, vcc, v4, v5, v4
	v_fma_f32 v9, -v6, v7, 1.0
	v_fmac_f32_e32 v7, v9, v7
	v_mul_f32_e32 v9, v8, v7
	v_fma_f32 v10, -v6, v9, v8
	v_fmac_f32_e32 v9, v10, v7
	v_fma_f32 v6, -v6, v9, v8
	v_div_fmas_f32 v6, v6, v7, v9
	v_div_fixup_f32 v4, v6, v5, v4
	ds_write_b32 v2, v4
	v_add_u32_e32 v2, 0x400, v2
	s_waitcnt vmcnt(25)
	v_mov_b32_e32 v4, v224
	v_mul_f32_e32 v5, 0xbfb8aa3b, v4
	v_exp_f32_e32 v5, v5
	s_nop 0
	v_add_f32_e32 v5, 1.0, v5
	v_div_scale_f32 v6, s[14:15], v5, v5, v4
	v_rcp_f32_e32 v7, v6
	v_div_scale_f32 v8, vcc, v4, v5, v4
	v_fma_f32 v9, -v6, v7, 1.0
	v_fmac_f32_e32 v7, v9, v7
	v_mul_f32_e32 v9, v8, v7
	v_fma_f32 v10, -v6, v9, v8
	v_fmac_f32_e32 v9, v10, v7
	v_fma_f32 v6, -v6, v9, v8
	v_div_fmas_f32 v6, v6, v7, v9
	v_div_fixup_f32 v4, v6, v5, v4
	ds_write_b32 v2, v4
	v_add_u32_e32 v2, 0x400, v2
	s_waitcnt vmcnt(24)
	v_mov_b32_e32 v4, v225
	v_mul_f32_e32 v5, 0xbfb8aa3b, v4
	v_exp_f32_e32 v5, v5
	s_nop 0
	v_add_f32_e32 v5, 1.0, v5
	v_div_scale_f32 v6, s[14:15], v5, v5, v4
	v_rcp_f32_e32 v7, v6
	v_div_scale_f32 v8, vcc, v4, v5, v4
	v_fma_f32 v9, -v6, v7, 1.0
	v_fmac_f32_e32 v7, v9, v7
	v_mul_f32_e32 v9, v8, v7
	v_fma_f32 v10, -v6, v9, v8
	v_fmac_f32_e32 v9, v10, v7
	v_fma_f32 v6, -v6, v9, v8
	v_div_fmas_f32 v6, v6, v7, v9
	v_div_fixup_f32 v4, v6, v5, v4
	ds_write_b32 v2, v4
	v_add_u32_e32 v2, 0x400, v2
	s_waitcnt vmcnt(23)
	v_mov_b32_e32 v4, v226
	v_mul_f32_e32 v5, 0xbfb8aa3b, v4
	v_exp_f32_e32 v5, v5
	s_nop 0
	v_add_f32_e32 v5, 1.0, v5
	v_div_scale_f32 v6, s[14:15], v5, v5, v4
	v_rcp_f32_e32 v7, v6
	v_div_scale_f32 v8, vcc, v4, v5, v4
	v_fma_f32 v9, -v6, v7, 1.0
	v_fmac_f32_e32 v7, v9, v7
	v_mul_f32_e32 v9, v8, v7
	v_fma_f32 v10, -v6, v9, v8
	v_fmac_f32_e32 v9, v10, v7
	v_fma_f32 v6, -v6, v9, v8
	v_div_fmas_f32 v6, v6, v7, v9
	v_div_fixup_f32 v4, v6, v5, v4
	ds_write_b32 v2, v4
	v_add_u32_e32 v2, 0x400, v2
	s_waitcnt vmcnt(22)
	v_mov_b32_e32 v4, v227
	v_mul_f32_e32 v5, 0xbfb8aa3b, v4
	v_exp_f32_e32 v5, v5
	s_nop 0
	v_add_f32_e32 v5, 1.0, v5
	v_div_scale_f32 v6, s[14:15], v5, v5, v4
	v_rcp_f32_e32 v7, v6
	v_div_scale_f32 v8, vcc, v4, v5, v4
	v_fma_f32 v9, -v6, v7, 1.0
	v_fmac_f32_e32 v7, v9, v7
	v_mul_f32_e32 v9, v8, v7
	v_fma_f32 v10, -v6, v9, v8
	v_fmac_f32_e32 v9, v10, v7
	v_fma_f32 v6, -v6, v9, v8
	v_div_fmas_f32 v6, v6, v7, v9
	v_div_fixup_f32 v4, v6, v5, v4
	ds_write_b32 v2, v4
	v_add_u32_e32 v2, 0x400, v2
	s_waitcnt vmcnt(21)
	v_mov_b32_e32 v4, v228
	v_mul_f32_e32 v5, 0xbfb8aa3b, v4
	v_exp_f32_e32 v5, v5
	s_nop 0
	v_add_f32_e32 v5, 1.0, v5
	v_div_scale_f32 v6, s[14:15], v5, v5, v4
	v_rcp_f32_e32 v7, v6
	v_div_scale_f32 v8, vcc, v4, v5, v4
	v_fma_f32 v9, -v6, v7, 1.0
	v_fmac_f32_e32 v7, v9, v7
	v_mul_f32_e32 v9, v8, v7
	v_fma_f32 v10, -v6, v9, v8
	v_fmac_f32_e32 v9, v10, v7
	v_fma_f32 v6, -v6, v9, v8
	v_div_fmas_f32 v6, v6, v7, v9
	v_div_fixup_f32 v4, v6, v5, v4
	ds_write_b32 v2, v4
	v_add_u32_e32 v2, 0x400, v2
	s_waitcnt vmcnt(20)
	v_mov_b32_e32 v4, v229
	v_mul_f32_e32 v5, 0xbfb8aa3b, v4
	v_exp_f32_e32 v5, v5
	s_nop 0
	v_add_f32_e32 v5, 1.0, v5
	v_div_scale_f32 v6, s[14:15], v5, v5, v4
	v_rcp_f32_e32 v7, v6
	v_div_scale_f32 v8, vcc, v4, v5, v4
	v_fma_f32 v9, -v6, v7, 1.0
	v_fmac_f32_e32 v7, v9, v7
	v_mul_f32_e32 v9, v8, v7
	v_fma_f32 v10, -v6, v9, v8
	v_fmac_f32_e32 v9, v10, v7
	v_fma_f32 v6, -v6, v9, v8
	v_div_fmas_f32 v6, v6, v7, v9
	v_div_fixup_f32 v4, v6, v5, v4
	ds_write_b32 v2, v4
	v_add_u32_e32 v2, 0x400, v2
	s_waitcnt vmcnt(19)
	v_mov_b32_e32 v4, v230
	v_mul_f32_e32 v5, 0xbfb8aa3b, v4
	v_exp_f32_e32 v5, v5
	s_nop 0
	v_add_f32_e32 v5, 1.0, v5
	v_div_scale_f32 v6, s[14:15], v5, v5, v4
	v_rcp_f32_e32 v7, v6
	v_div_scale_f32 v8, vcc, v4, v5, v4
	v_fma_f32 v9, -v6, v7, 1.0
	v_fmac_f32_e32 v7, v9, v7
	v_mul_f32_e32 v9, v8, v7
	v_fma_f32 v10, -v6, v9, v8
	v_fmac_f32_e32 v9, v10, v7
	v_fma_f32 v6, -v6, v9, v8
	v_div_fmas_f32 v6, v6, v7, v9
	v_div_fixup_f32 v4, v6, v5, v4
	ds_write_b32 v2, v4
	v_add_u32_e32 v2, 0x400, v2
	s_waitcnt vmcnt(18)
	v_mov_b32_e32 v4, v231
	v_mul_f32_e32 v5, 0xbfb8aa3b, v4
	v_exp_f32_e32 v5, v5
	s_nop 0
	v_add_f32_e32 v5, 1.0, v5
	v_div_scale_f32 v6, s[14:15], v5, v5, v4
	v_rcp_f32_e32 v7, v6
	v_div_scale_f32 v8, vcc, v4, v5, v4
	v_fma_f32 v9, -v6, v7, 1.0
	v_fmac_f32_e32 v7, v9, v7
	v_mul_f32_e32 v9, v8, v7
	v_fma_f32 v10, -v6, v9, v8
	v_fmac_f32_e32 v9, v10, v7
	v_fma_f32 v6, -v6, v9, v8
	v_div_fmas_f32 v6, v6, v7, v9
	v_div_fixup_f32 v4, v6, v5, v4
	ds_write_b32 v2, v4
	v_add_u32_e32 v2, 0x400, v2
	s_waitcnt vmcnt(17)
	v_mov_b32_e32 v4, v232
	v_mul_f32_e32 v5, 0xbfb8aa3b, v4
	v_exp_f32_e32 v5, v5
	s_nop 0
	v_add_f32_e32 v5, 1.0, v5
	v_div_scale_f32 v6, s[14:15], v5, v5, v4
	v_rcp_f32_e32 v7, v6
	v_div_scale_f32 v8, vcc, v4, v5, v4
	v_fma_f32 v9, -v6, v7, 1.0
	v_fmac_f32_e32 v7, v9, v7
	v_mul_f32_e32 v9, v8, v7
	v_fma_f32 v10, -v6, v9, v8
	v_fmac_f32_e32 v9, v10, v7
	v_fma_f32 v6, -v6, v9, v8
	v_div_fmas_f32 v6, v6, v7, v9
	v_div_fixup_f32 v4, v6, v5, v4
	ds_write_b32 v2, v4
	v_add_u32_e32 v2, 0x400, v2
	s_waitcnt vmcnt(16)
	v_mov_b32_e32 v4, v233
	v_mul_f32_e32 v5, 0xbfb8aa3b, v4
	v_exp_f32_e32 v5, v5
	s_nop 0
	v_add_f32_e32 v5, 1.0, v5
	v_div_scale_f32 v6, s[14:15], v5, v5, v4
	v_rcp_f32_e32 v7, v6
	v_div_scale_f32 v8, vcc, v4, v5, v4
	v_fma_f32 v9, -v6, v7, 1.0
	v_fmac_f32_e32 v7, v9, v7
	v_mul_f32_e32 v9, v8, v7
	v_fma_f32 v10, -v6, v9, v8
	v_fmac_f32_e32 v9, v10, v7
	v_fma_f32 v6, -v6, v9, v8
	v_div_fmas_f32 v6, v6, v7, v9
	v_div_fixup_f32 v4, v6, v5, v4
	ds_write_b32 v2, v4
	v_add_u32_e32 v2, 0x400, v2
	s_waitcnt vmcnt(15)
	v_mov_b32_e32 v4, v234
	v_mul_f32_e32 v5, 0xbfb8aa3b, v4
	v_exp_f32_e32 v5, v5
	s_nop 0
	v_add_f32_e32 v5, 1.0, v5
	v_div_scale_f32 v6, s[14:15], v5, v5, v4
	v_rcp_f32_e32 v7, v6
	v_div_scale_f32 v8, vcc, v4, v5, v4
	v_fma_f32 v9, -v6, v7, 1.0
	v_fmac_f32_e32 v7, v9, v7
	v_mul_f32_e32 v9, v8, v7
	v_fma_f32 v10, -v6, v9, v8
	v_fmac_f32_e32 v9, v10, v7
	v_fma_f32 v6, -v6, v9, v8
	v_div_fmas_f32 v6, v6, v7, v9
	v_div_fixup_f32 v4, v6, v5, v4
	ds_write_b32 v2, v4
	v_add_u32_e32 v2, 0x400, v2
	s_waitcnt vmcnt(14)
	v_mov_b32_e32 v4, v235
	v_mul_f32_e32 v5, 0xbfb8aa3b, v4
	v_exp_f32_e32 v5, v5
	s_nop 0
	v_add_f32_e32 v5, 1.0, v5
	v_div_scale_f32 v6, s[14:15], v5, v5, v4
	v_rcp_f32_e32 v7, v6
	v_div_scale_f32 v8, vcc, v4, v5, v4
	v_fma_f32 v9, -v6, v7, 1.0
	v_fmac_f32_e32 v7, v9, v7
	v_mul_f32_e32 v9, v8, v7
	v_fma_f32 v10, -v6, v9, v8
	v_fmac_f32_e32 v9, v10, v7
	v_fma_f32 v6, -v6, v9, v8
	v_div_fmas_f32 v6, v6, v7, v9
	v_div_fixup_f32 v4, v6, v5, v4
	ds_write_b32 v2, v4
	v_add_u32_e32 v2, 0x400, v2
	s_waitcnt vmcnt(13)
	v_mov_b32_e32 v4, v236
	v_mul_f32_e32 v5, 0xbfb8aa3b, v4
	v_exp_f32_e32 v5, v5
	s_nop 0
	v_add_f32_e32 v5, 1.0, v5
	v_div_scale_f32 v6, s[14:15], v5, v5, v4
	v_rcp_f32_e32 v7, v6
	v_div_scale_f32 v8, vcc, v4, v5, v4
	v_fma_f32 v9, -v6, v7, 1.0
	v_fmac_f32_e32 v7, v9, v7
	v_mul_f32_e32 v9, v8, v7
	v_fma_f32 v10, -v6, v9, v8
	v_fmac_f32_e32 v9, v10, v7
	v_fma_f32 v6, -v6, v9, v8
	v_div_fmas_f32 v6, v6, v7, v9
	v_div_fixup_f32 v4, v6, v5, v4
	ds_write_b32 v2, v4
	v_add_u32_e32 v2, 0x400, v2
	s_waitcnt vmcnt(12)
	v_mov_b32_e32 v4, v237
	v_mul_f32_e32 v5, 0xbfb8aa3b, v4
	v_exp_f32_e32 v5, v5
	s_nop 0
	v_add_f32_e32 v5, 1.0, v5
	v_div_scale_f32 v6, s[14:15], v5, v5, v4
	v_rcp_f32_e32 v7, v6
	v_div_scale_f32 v8, vcc, v4, v5, v4
	v_fma_f32 v9, -v6, v7, 1.0
	v_fmac_f32_e32 v7, v9, v7
	v_mul_f32_e32 v9, v8, v7
	v_fma_f32 v10, -v6, v9, v8
	v_fmac_f32_e32 v9, v10, v7
	v_fma_f32 v6, -v6, v9, v8
	v_div_fmas_f32 v6, v6, v7, v9
	v_div_fixup_f32 v4, v6, v5, v4
	ds_write_b32 v2, v4
	v_add_u32_e32 v2, 0x400, v2
	s_waitcnt vmcnt(11)
	v_mov_b32_e32 v4, v238
	v_mul_f32_e32 v5, 0xbfb8aa3b, v4
	v_exp_f32_e32 v5, v5
	s_nop 0
	v_add_f32_e32 v5, 1.0, v5
	v_div_scale_f32 v6, s[14:15], v5, v5, v4
	v_rcp_f32_e32 v7, v6
	v_div_scale_f32 v8, vcc, v4, v5, v4
	v_fma_f32 v9, -v6, v7, 1.0
	v_fmac_f32_e32 v7, v9, v7
	v_mul_f32_e32 v9, v8, v7
	v_fma_f32 v10, -v6, v9, v8
	v_fmac_f32_e32 v9, v10, v7
	v_fma_f32 v6, -v6, v9, v8
	v_div_fmas_f32 v6, v6, v7, v9
	v_div_fixup_f32 v4, v6, v5, v4
	ds_write_b32 v2, v4
	v_add_u32_e32 v2, 0x400, v2
	s_waitcnt vmcnt(10)
	v_mov_b32_e32 v4, v239
	v_mul_f32_e32 v5, 0xbfb8aa3b, v4
	v_exp_f32_e32 v5, v5
	s_nop 0
	v_add_f32_e32 v5, 1.0, v5
	v_div_scale_f32 v6, s[14:15], v5, v5, v4
	v_rcp_f32_e32 v7, v6
	v_div_scale_f32 v8, vcc, v4, v5, v4
	v_fma_f32 v9, -v6, v7, 1.0
	v_fmac_f32_e32 v7, v9, v7
	v_mul_f32_e32 v9, v8, v7
	v_fma_f32 v10, -v6, v9, v8
	v_fmac_f32_e32 v9, v10, v7
	v_fma_f32 v6, -v6, v9, v8
	v_div_fmas_f32 v6, v6, v7, v9
	v_div_fixup_f32 v4, v6, v5, v4
	ds_write_b32 v2, v4
	v_add_u32_e32 v2, 0x400, v2
	s_waitcnt vmcnt(9)
	v_mov_b32_e32 v4, v240
	v_mul_f32_e32 v5, 0xbfb8aa3b, v4
	v_exp_f32_e32 v5, v5
	s_nop 0
	v_add_f32_e32 v5, 1.0, v5
	v_div_scale_f32 v6, s[14:15], v5, v5, v4
	v_rcp_f32_e32 v7, v6
	v_div_scale_f32 v8, vcc, v4, v5, v4
	v_fma_f32 v9, -v6, v7, 1.0
	v_fmac_f32_e32 v7, v9, v7
	v_mul_f32_e32 v9, v8, v7
	v_fma_f32 v10, -v6, v9, v8
	v_fmac_f32_e32 v9, v10, v7
	v_fma_f32 v6, -v6, v9, v8
	v_div_fmas_f32 v6, v6, v7, v9
	v_div_fixup_f32 v4, v6, v5, v4
	ds_write_b32 v2, v4
	v_add_u32_e32 v2, 0x400, v2
	s_waitcnt vmcnt(8)
	v_mov_b32_e32 v4, v241
	v_mul_f32_e32 v5, 0xbfb8aa3b, v4
	v_exp_f32_e32 v5, v5
	s_nop 0
	v_add_f32_e32 v5, 1.0, v5
	v_div_scale_f32 v6, s[14:15], v5, v5, v4
	v_rcp_f32_e32 v7, v6
	v_div_scale_f32 v8, vcc, v4, v5, v4
	v_fma_f32 v9, -v6, v7, 1.0
	v_fmac_f32_e32 v7, v9, v7
	v_mul_f32_e32 v9, v8, v7
	v_fma_f32 v10, -v6, v9, v8
	v_fmac_f32_e32 v9, v10, v7
	v_fma_f32 v6, -v6, v9, v8
	v_div_fmas_f32 v6, v6, v7, v9
	v_div_fixup_f32 v4, v6, v5, v4
	ds_write_b32 v2, v4
	v_add_u32_e32 v2, 0x400, v2
	s_waitcnt vmcnt(7)
	v_mov_b32_e32 v4, v242
	v_mul_f32_e32 v5, 0xbfb8aa3b, v4
	v_exp_f32_e32 v5, v5
	s_nop 0
	v_add_f32_e32 v5, 1.0, v5
	v_div_scale_f32 v6, s[14:15], v5, v5, v4
	v_rcp_f32_e32 v7, v6
	v_div_scale_f32 v8, vcc, v4, v5, v4
	v_fma_f32 v9, -v6, v7, 1.0
	v_fmac_f32_e32 v7, v9, v7
	v_mul_f32_e32 v9, v8, v7
	v_fma_f32 v10, -v6, v9, v8
	v_fmac_f32_e32 v9, v10, v7
	v_fma_f32 v6, -v6, v9, v8
	v_div_fmas_f32 v6, v6, v7, v9
	v_div_fixup_f32 v4, v6, v5, v4
	ds_write_b32 v2, v4
	v_add_u32_e32 v2, 0x400, v2
	s_waitcnt vmcnt(6)
	v_mov_b32_e32 v4, v243
	v_mul_f32_e32 v5, 0xbfb8aa3b, v4
	v_exp_f32_e32 v5, v5
	s_nop 0
	v_add_f32_e32 v5, 1.0, v5
	v_div_scale_f32 v6, s[14:15], v5, v5, v4
	v_rcp_f32_e32 v7, v6
	v_div_scale_f32 v8, vcc, v4, v5, v4
	v_fma_f32 v9, -v6, v7, 1.0
	v_fmac_f32_e32 v7, v9, v7
	v_mul_f32_e32 v9, v8, v7
	v_fma_f32 v10, -v6, v9, v8
	v_fmac_f32_e32 v9, v10, v7
	v_fma_f32 v6, -v6, v9, v8
	v_div_fmas_f32 v6, v6, v7, v9
	v_div_fixup_f32 v4, v6, v5, v4
	ds_write_b32 v2, v4
	v_add_u32_e32 v2, 0x400, v2
	s_waitcnt vmcnt(5)
	v_mov_b32_e32 v4, v244
	v_mul_f32_e32 v5, 0xbfb8aa3b, v4
	v_exp_f32_e32 v5, v5
	s_nop 0
	v_add_f32_e32 v5, 1.0, v5
	v_div_scale_f32 v6, s[14:15], v5, v5, v4
	v_rcp_f32_e32 v7, v6
	v_div_scale_f32 v8, vcc, v4, v5, v4
	v_fma_f32 v9, -v6, v7, 1.0
	v_fmac_f32_e32 v7, v9, v7
	v_mul_f32_e32 v9, v8, v7
	v_fma_f32 v10, -v6, v9, v8
	v_fmac_f32_e32 v9, v10, v7
	v_fma_f32 v6, -v6, v9, v8
	v_div_fmas_f32 v6, v6, v7, v9
	v_div_fixup_f32 v4, v6, v5, v4
	ds_write_b32 v2, v4
	v_add_u32_e32 v2, 0x400, v2
	s_waitcnt vmcnt(4)
	v_mov_b32_e32 v4, v245
	v_mul_f32_e32 v5, 0xbfb8aa3b, v4
	v_exp_f32_e32 v5, v5
	s_nop 0
	v_add_f32_e32 v5, 1.0, v5
	v_div_scale_f32 v6, s[14:15], v5, v5, v4
	v_rcp_f32_e32 v7, v6
	v_div_scale_f32 v8, vcc, v4, v5, v4
	v_fma_f32 v9, -v6, v7, 1.0
	v_fmac_f32_e32 v7, v9, v7
	v_mul_f32_e32 v9, v8, v7
	v_fma_f32 v10, -v6, v9, v8
	v_fmac_f32_e32 v9, v10, v7
	v_fma_f32 v6, -v6, v9, v8
	v_div_fmas_f32 v6, v6, v7, v9
	v_div_fixup_f32 v4, v6, v5, v4
	ds_write_b32 v2, v4
	v_add_u32_e32 v2, 0x400, v2
	s_waitcnt vmcnt(3)
	v_mov_b32_e32 v4, v246
	v_mul_f32_e32 v5, 0xbfb8aa3b, v4
	v_exp_f32_e32 v5, v5
	s_nop 0
	v_add_f32_e32 v5, 1.0, v5
	v_div_scale_f32 v6, s[14:15], v5, v5, v4
	v_rcp_f32_e32 v7, v6
	v_div_scale_f32 v8, vcc, v4, v5, v4
	v_fma_f32 v9, -v6, v7, 1.0
	v_fmac_f32_e32 v7, v9, v7
	v_mul_f32_e32 v9, v8, v7
	v_fma_f32 v10, -v6, v9, v8
	v_fmac_f32_e32 v9, v10, v7
	v_fma_f32 v6, -v6, v9, v8
	v_div_fmas_f32 v6, v6, v7, v9
	v_div_fixup_f32 v4, v6, v5, v4
	ds_write_b32 v2, v4
	v_add_u32_e32 v2, 0x400, v2
	s_waitcnt vmcnt(2)
	v_mov_b32_e32 v4, v247
	v_mul_f32_e32 v5, 0xbfb8aa3b, v4
	v_exp_f32_e32 v5, v5
	s_nop 0
	v_add_f32_e32 v5, 1.0, v5
	v_div_scale_f32 v6, s[14:15], v5, v5, v4
	v_rcp_f32_e32 v7, v6
	v_div_scale_f32 v8, vcc, v4, v5, v4
	v_fma_f32 v9, -v6, v7, 1.0
	v_fmac_f32_e32 v7, v9, v7
	v_mul_f32_e32 v9, v8, v7
	v_fma_f32 v10, -v6, v9, v8
	v_fmac_f32_e32 v9, v10, v7
	v_fma_f32 v6, -v6, v9, v8
	v_div_fmas_f32 v6, v6, v7, v9
	v_div_fixup_f32 v4, v6, v5, v4
	ds_write_b32 v2, v4
	v_add_u32_e32 v2, 0x400, v2
	s_waitcnt vmcnt(1)
	v_mov_b32_e32 v4, v248
	v_mul_f32_e32 v5, 0xbfb8aa3b, v4
	v_exp_f32_e32 v5, v5
	s_nop 0
	v_add_f32_e32 v5, 1.0, v5
	v_div_scale_f32 v6, s[14:15], v5, v5, v4
	v_rcp_f32_e32 v7, v6
	v_div_scale_f32 v8, vcc, v4, v5, v4
	v_fma_f32 v9, -v6, v7, 1.0
	v_fmac_f32_e32 v7, v9, v7
	v_mul_f32_e32 v9, v8, v7
	v_fma_f32 v10, -v6, v9, v8
	v_fmac_f32_e32 v9, v10, v7
	v_fma_f32 v6, -v6, v9, v8
	v_div_fmas_f32 v6, v6, v7, v9
	v_div_fixup_f32 v4, v6, v5, v4
	ds_write_b32 v2, v4
	v_add_u32_e32 v2, 0x400, v2
	s_waitcnt vmcnt(0)
	v_mov_b32_e32 v4, v249
	v_mul_f32_e32 v5, 0xbfb8aa3b, v4
	v_exp_f32_e32 v5, v5
	s_nop 0
	v_add_f32_e32 v5, 1.0, v5
	v_div_scale_f32 v6, s[14:15], v5, v5, v4
	v_rcp_f32_e32 v7, v6
	v_div_scale_f32 v8, vcc, v4, v5, v4
	v_fma_f32 v9, -v6, v7, 1.0
	v_fmac_f32_e32 v7, v9, v7
	v_mul_f32_e32 v9, v8, v7
	v_fma_f32 v10, -v6, v9, v8
	v_fmac_f32_e32 v9, v10, v7
	v_fma_f32 v6, -v6, v9, v8
	v_div_fmas_f32 v6, v6, v7, v9
	v_div_fixup_f32 v4, v6, v5, v4
	ds_write_b32 v2, v4
	v_add_u32_e32 v2, 0x400, v2
